# attention: lazy online-softmax rescale - keep the running max unless a row max grows by more than 8 (log2 units); exact softmax, f32 accumulation unchanged
# speedup vs baseline: 1.0089x; 1.0061x over previous
; DI float shx(float v, int o, int lane) { return __int_as_float(__builtin_amdgcn_ds_bpermute((lane ^ o) << 2, __float_as_int(v))); }
; DI int crow(int i, int hh) { return (i & 3) + 8 * (i >> 2) + 4 * hh; }
; #define MFMA32(a, b, c) __builtin_amdgcn_mfma_f32_32x32x16_bf16((a), (b), (c), 0, 0, 0)
; DI void attn_item(CArgs& a, LAS unsigned char* lds, int l, int b, int h, int qb, int tid_, int wave, int lane_) {
;     ...
;             for (int ks = 0; ks < 8; ++ks) p = MFMA32(lds_b128(Ks + (32 * kt + r) * 136 + 16 * ks + 8 * hh), qf[ks], p);
; #pragma unroll
;             for (int ks = 0; ks < 4; ++ks) p = MFMA32(lds_b128(Rs + (32 * kt + r) * 72 + 16 * ks + 8 * hh), qf[8 + ks], p);
;             if (j >= 4 * qb) {
; #pragma unroll
;                 for (int i = 0; i < 16; ++i) { const int key = 64 * j + 32 * kt + crow(i, hh); if (key > qloc) p[i] = -INFINITY; } }
;             float tmax = p[0];
; #pragma unroll
;             for (int i = 1; i < 16; ++i) tmax = fmaxf(tmax, p[i]);
;             tmax = fmaxf(tmax, shx(tmax, 32, lane));
;             const float m_new = fmaxf(m_run, tmax), alpha = __builtin_amdgcn_exp2f(m_run - m_new); m_run = m_new;
;             float rsum = 0.f;
; #pragma unroll
;             for (int i = 0; i < 16; ++i) { const float e = __builtin_amdgcn_exp2f(p[i] - m_new); p[i] = e; rsum += e; }
;             l_run = l_run * alpha + rsum;
;             if (__any(alpha != 1.f)) {
;                 if (hh == 0) scr[r] = alpha;
;                 asm volatile("s_waitcnt lgkmcnt(0)" ::: "memory");
; #pragma unroll
;                 for (int i = 0; i < 16; ++i) { const float ai = scr[crow(i, hh)]; o[0][i] *= ai; o[1][i] *= ai; o[2][i] *= ai; o[3][i] *= ai; }
;             }
.LBB0_302:
	v_max_f32_e32 v205, v65, v65
	v_max_f32_e32 v206, v64, v64
	v_max_f32_e32 v205, v206, v205
	s_waitcnt lgkmcnt(3)
	v_mfma_f32_32x32x16_bf16 v[82:97], v[216:219], v[114:117], v[82:97]
	ds_read_b128 v[216:219], v210 offset:22016
	v_max3_f32 v205, v205, v66, v67
	v_max3_f32 v205, v205, v68, v69
	v_max3_f32 v205, v205, v70, v71
	v_max3_f32 v205, v205, v72, v73
	s_waitcnt lgkmcnt(3)
	v_mfma_f32_32x32x16_bf16 v[82:97], v[238:241], v[118:121], v[82:97]
	ds_read_b128 v[238:241], v210 offset:22048
	v_max3_f32 v205, v205, v74, v75
	v_max3_f32 v205, v205, v76, v77
	v_max3_f32 v205, v205, v78, v79
	ds_bpermute_b32 v206, v198, v205
	s_waitcnt lgkmcnt(4)
	v_mfma_f32_32x32x16_bf16 v[82:97], v[242:245], v[122:125], v[82:97]
	ds_read_b128 v[242:245], v210 offset:22080
	s_waitcnt lgkmcnt(4)
	v_mfma_f32_32x32x16_bf16 v[82:97], v[246:249], v[126:129], v[82:97]
	ds_read_b128 v[246:249], v210 offset:22112
	s_waitcnt lgkmcnt(2)
	v_max3_f32 v211, v204, v205, v206
	v_sub_f32_e32 v206, v204, v211
	v_cmp_gt_f32_e32 vcc, 0xc1000000, v206
	s_cbranch_vccz .Llazy0_0
	v_exp_f32_e32 v206, v206
	s_nop 0
	s_and_saveexec_b64 s[4:5], s[6:7]
	ds_write_b32 v197, v206
	s_or_b64 exec, exec, s[4:5]
	s_waitcnt lgkmcnt(0)
	v_add_u32_e32 v204, s27, v80
	ds_read_b128 v[212:215], v204 offset:96
	ds_read_b128 v[226:229], v204 offset:64
	ds_read_b128 v[230:233], v204 offset:32
	ds_read_b128 v[234:237], v204
	s_mov_b64 s[58:59], 0x10000
	s_waitcnt lgkmcnt(3)
	v_pk_mul_f32 v[12:13], v[12:13], v[212:213]
	s_waitcnt lgkmcnt(2)
	v_pk_mul_f32 v[8:9], v[8:9], v[226:227]
	s_waitcnt lgkmcnt(1)
	v_pk_mul_f32 v[4:5], v[4:5], v[230:231]
	v_pk_mul_f32 v[14:15], v[14:15], v[214:215]
	v_pk_mul_f32 v[10:11], v[10:11], v[228:229]
	v_pk_mul_f32 v[6:7], v[6:7], v[232:233]
	s_waitcnt lgkmcnt(0)
	v_pk_mul_f32 v[2:3], v[2:3], v[236:237]
	v_pk_mul_f32 v[0:1], v[0:1], v[234:235]
	v_pk_mul_f32 v[28:29], v[28:29], v[212:213]
	v_pk_mul_f32 v[24:25], v[24:25], v[226:227]
	v_pk_mul_f32 v[20:21], v[20:21], v[230:231]
	v_pk_mul_f32 v[30:31], v[30:31], v[214:215]
	v_pk_mul_f32 v[26:27], v[26:27], v[228:229]
	v_pk_mul_f32 v[22:23], v[22:23], v[232:233]
	v_pk_mul_f32 v[18:19], v[18:19], v[236:237]
	v_pk_mul_f32 v[16:17], v[16:17], v[234:235]
	v_pk_mul_f32 v[44:45], v[44:45], v[212:213]
	v_pk_mul_f32 v[40:41], v[40:41], v[226:227]
	v_pk_mul_f32 v[36:37], v[36:37], v[230:231]
	v_pk_mul_f32 v[46:47], v[46:47], v[214:215]
	v_pk_mul_f32 v[42:43], v[42:43], v[228:229]
	v_pk_mul_f32 v[38:39], v[38:39], v[232:233]
	v_pk_mul_f32 v[34:35], v[34:35], v[236:237]
	v_pk_mul_f32 v[32:33], v[32:33], v[234:235]
	v_pk_mul_f32 v[60:61], v[60:61], v[212:213]
	v_pk_mul_f32 v[56:57], v[56:57], v[226:227]
	v_pk_mul_f32 v[52:53], v[52:53], v[230:231]
	v_pk_mul_f32 v[62:63], v[62:63], v[214:215]
	v_pk_mul_f32 v[58:59], v[58:59], v[228:229]
	v_pk_mul_f32 v[54:55], v[54:55], v[232:233]
	v_pk_mul_f32 v[50:51], v[50:51], v[236:237]
	v_pk_mul_f32 v[48:49], v[48:49], v[234:235]

; DI float shx(float v, int o, int lane) { return __int_as_float(__builtin_amdgcn_ds_bpermute((lane ^ o) << 2, __float_as_int(v))); }
; DI int crow(int i, int hh) { return (i & 3) + 8 * (i >> 2) + 4 * hh; }
; #define MFMA32(a, b, c) __builtin_amdgcn_mfma_f32_32x32x16_bf16((a), (b), (c), 0, 0, 0)
; DI void attn_item(CArgs& a, LAS unsigned char* lds, int l, int b, int h, int qb, int tid_, int wave, int lane_) {
;     ...
;             for (int ks = 0; ks < 8; ++ks) p = MFMA32(lds_b128(Ks + (32 * kt + r) * 136 + 16 * ks + 8 * hh), qf[ks], p);
; #pragma unroll
;             for (int ks = 0; ks < 4; ++ks) p = MFMA32(lds_b128(Rs + (32 * kt + r) * 72 + 16 * ks + 8 * hh), qf[8 + ks], p);
;             if (j >= 4 * qb) {
; #pragma unroll
;                 for (int i = 0; i < 16; ++i) { const int key = 64 * j + 32 * kt + crow(i, hh); if (key > qloc) p[i] = -INFINITY; } }
;             float tmax = p[0];
; #pragma unroll
;             for (int i = 1; i < 16; ++i) tmax = fmaxf(tmax, p[i]);
;             tmax = fmaxf(tmax, shx(tmax, 32, lane));
;             const float m_new = fmaxf(m_run, tmax), alpha = __builtin_amdgcn_exp2f(m_run - m_new); m_run = m_new;
;             float rsum = 0.f;
; #pragma unroll
;             for (int i = 0; i < 16; ++i) { const float e = __builtin_amdgcn_exp2f(p[i] - m_new); p[i] = e; rsum += e; }
;             l_run = l_run * alpha + rsum;
;             if (__any(alpha != 1.f)) {
;                 if (hh == 0) scr[r] = alpha;
;                 asm volatile("s_waitcnt lgkmcnt(0)" ::: "memory");
; #pragma unroll
;                 for (int i = 0; i < 16; ++i) { const float ai = scr[crow(i, hh)]; o[0][i] *= ai; o[1][i] *= ai; o[2][i] *= ai; o[3][i] *= ai; }
;             }
.LBB0_308:
	v_max_f32_e32 v204, v83, v83
	v_max_f32_e32 v208, v82, v82
	v_max_f32_e32 v204, v208, v204
	s_waitcnt lgkmcnt(3)
	v_mfma_f32_32x32x16_bf16 v[0:15], v[72:75], v[68:71], v[0:15]
	v_max3_f32 v204, v204, v84, v85
	v_max3_f32 v204, v204, v86, v87
	v_max3_f32 v204, v204, v88, v89
	v_max3_f32 v204, v204, v90, v91
	s_waitcnt lgkmcnt(2)
	v_mfma_f32_32x32x16_bf16 v[16:31], v[72:75], v[76:79], v[16:31]
	v_max3_f32 v204, v204, v92, v93
	v_max3_f32 v204, v204, v94, v95
	v_max3_f32 v204, v204, v96, v97
	ds_bpermute_b32 v208, v198, v204
	s_waitcnt lgkmcnt(2)
	v_mfma_f32_32x32x16_bf16 v[32:47], v[72:75], v[216:219], v[32:47]
	s_waitcnt lgkmcnt(1)
	v_mfma_f32_32x32x16_bf16 v[48:63], v[72:75], v[238:241], v[48:63]
	s_waitcnt lgkmcnt(0)
	v_max3_f32 v204, v211, v204, v208
	v_sub_f32_e32 v208, v211, v204
	v_cmp_gt_f32_e32 vcc, 0xc1000000, v208
	s_cbranch_vccz .Llazy1_0
	v_exp_f32_e32 v208, v208
	s_nop 0
	s_and_saveexec_b64 s[0:1], s[6:7]
	ds_write_b32 v197, v208
	s_or_b64 exec, exec, s[0:1]
	s_waitcnt lgkmcnt(0)
	v_add_u32_e32 v209, s27, v80
	ds_read_b128 v[238:241], v209 offset:96
	ds_read_b128 v[242:245], v209 offset:64
	ds_read_b128 v[246:249], v209 offset:32
	ds_read_b128 v[216:219], v209
	s_waitcnt lgkmcnt(3)
	v_pk_mul_f32 v[12:13], v[12:13], v[238:239]
	s_waitcnt lgkmcnt(2)
	v_pk_mul_f32 v[8:9], v[8:9], v[242:243]
	s_waitcnt lgkmcnt(1)
	v_pk_mul_f32 v[4:5], v[4:5], v[246:247]
	v_pk_mul_f32 v[14:15], v[14:15], v[240:241]
	v_pk_mul_f32 v[10:11], v[10:11], v[244:245]
	v_pk_mul_f32 v[6:7], v[6:7], v[248:249]
	s_waitcnt lgkmcnt(0)
	v_pk_mul_f32 v[2:3], v[2:3], v[218:219]
	v_pk_mul_f32 v[0:1], v[0:1], v[216:217]
	v_pk_mul_f32 v[28:29], v[28:29], v[238:239]
	v_pk_mul_f32 v[24:25], v[24:25], v[242:243]
	v_pk_mul_f32 v[20:21], v[20:21], v[246:247]
	v_pk_mul_f32 v[30:31], v[30:31], v[240:241]
	v_pk_mul_f32 v[26:27], v[26:27], v[244:245]
	v_pk_mul_f32 v[22:23], v[22:23], v[248:249]
	v_pk_mul_f32 v[18:19], v[18:19], v[218:219]
	v_pk_mul_f32 v[16:17], v[16:17], v[216:217]
	v_pk_mul_f32 v[44:45], v[44:45], v[238:239]
	v_pk_mul_f32 v[40:41], v[40:41], v[242:243]
	v_pk_mul_f32 v[36:37], v[36:37], v[246:247]
	v_pk_mul_f32 v[46:47], v[46:47], v[240:241]
	v_pk_mul_f32 v[42:43], v[42:43], v[244:245]
	v_pk_mul_f32 v[38:39], v[38:39], v[248:249]
	v_pk_mul_f32 v[34:35], v[34:35], v[218:219]
	v_pk_mul_f32 v[32:33], v[32:33], v[216:217]
	v_pk_mul_f32 v[60:61], v[60:61], v[238:239]
	v_pk_mul_f32 v[56:57], v[56:57], v[242:243]
	v_pk_mul_f32 v[52:53], v[52:53], v[246:247]
	v_pk_mul_f32 v[62:63], v[62:63], v[240:241]
	v_pk_mul_f32 v[58:59], v[58:59], v[244:245]
	v_pk_mul_f32 v[54:55], v[54:55], v[248:249]
	v_pk_mul_f32 v[50:51], v[50:51], v[218:219]
	v_pk_mul_f32 v[48:49], v[48:49], v[216:217]

; DI int crow(int i, int hh) { return (i & 3) + 8 * (i >> 2) + 4 * hh; }
; DI void attn_item(CArgs& a, LAS unsigned char* lds, int l, int b, int h, int qb, int tid_, int wave, int lane_) {
;     ...
;             const float m_new = fmaxf(m_run, tmax), alpha = __builtin_amdgcn_exp2f(m_run - m_new); m_run = m_new;
;             float rsum = 0.f;
; #pragma unroll
;             for (int i = 0; i < 16; ++i) { const float e = __builtin_amdgcn_exp2f(p[i] - m_new); p[i] = e; rsum += e; }
;             l_run = l_run * alpha + rsum;
;             if (__any(alpha != 1.f)) {
;                 if (hh == 0) scr[r] = alpha;
;                 asm volatile("s_waitcnt lgkmcnt(0)" ::: "memory");
; #pragma unroll
;                 for (int i = 0; i < 16; ++i) { const float ai = scr[crow(i, hh)]; o[0][i] *= ai; o[1][i] *= ai; o[2][i] *= ai; o[3][i] *= ai; }
;             }
.Llazy0_0:
	v_mov_b32_e32 v211, v204
	v_mov_b32_e32 v206, 1.0
	s_branch .LBB0_306
.Llazy1_0:
	v_mov_b32_e32 v204, v211
	v_mov_b32_e32 v208, 1.0
	s_branch .LBB0_312

; DI float shx(float v, int o, int lane) { return __int_as_float(__builtin_amdgcn_ds_bpermute((lane ^ o) << 2, __float_as_int(v))); }
; DI int crow(int i, int hh) { return (i & 3) + 8 * (i >> 2) + 4 * hh; }
; #define MFMA32(a, b, c) __builtin_amdgcn_mfma_f32_32x32x16_bf16((a), (b), (c), 0, 0, 0)
; DI void attn_item(CArgs& a, LAS unsigned char* lds, int l, int b, int h, int qb, int tid_, int wave, int lane_) {
;     ...
;             for (int ks = 0; ks < 8; ++ks) p = MFMA32(lds_b128(Ks + (32 * kt + r) * 136 + 16 * ks + 8 * hh), qf[ks], p);
; #pragma unroll
;             for (int ks = 0; ks < 4; ++ks) p = MFMA32(lds_b128(Rs + (32 * kt + r) * 72 + 16 * ks + 8 * hh), qf[8 + ks], p);
;             if (j >= 4 * qb) {
; #pragma unroll
;                 for (int i = 0; i < 16; ++i) { const int key = 64 * j + 32 * kt + crow(i, hh); if (key > qloc) p[i] = -INFINITY; } }
;             float tmax = p[0];
; #pragma unroll
;             for (int i = 1; i < 16; ++i) tmax = fmaxf(tmax, p[i]);
;             tmax = fmaxf(tmax, shx(tmax, 32, lane));
;             const float m_new = fmaxf(m_run, tmax), alpha = __builtin_amdgcn_exp2f(m_run - m_new); m_run = m_new;
;             float rsum = 0.f;
; #pragma unroll
;             for (int i = 0; i < 16; ++i) { const float e = __builtin_amdgcn_exp2f(p[i] - m_new); p[i] = e; rsum += e; }
;             l_run = l_run * alpha + rsum;
;             if (__any(alpha != 1.f)) {
;                 if (hh == 0) scr[r] = alpha;
;                 asm volatile("s_waitcnt lgkmcnt(0)" ::: "memory");
; #pragma unroll
;                 for (int i = 0; i < 16; ++i) { const float ai = scr[crow(i, hh)]; o[0][i] *= ai; o[1][i] *= ai; o[2][i] *= ai; o[3][i] *= ai; }
;             }
.LBB0_323:
	v_max_f32_e32 v205, v65, v65
	v_max_f32_e32 v206, v64, v64
	v_max_f32_e32 v205, v206, v205
	s_waitcnt lgkmcnt(3)
	v_mfma_f32_32x32x16_bf16 v[82:97], v[216:219], v[114:117], v[82:97]
	ds_read_b128 v[216:219], v210 offset:22016
	v_max3_f32 v205, v205, v66, v67
	v_max3_f32 v205, v205, v68, v69
	v_max3_f32 v205, v205, v70, v71
	v_max3_f32 v205, v205, v72, v73
	s_waitcnt lgkmcnt(3)
	v_mfma_f32_32x32x16_bf16 v[82:97], v[238:241], v[118:121], v[82:97]
	ds_read_b128 v[238:241], v210 offset:22048
	v_max3_f32 v205, v205, v74, v75
	v_max3_f32 v205, v205, v76, v77
	v_max3_f32 v205, v205, v78, v79
	ds_bpermute_b32 v206, v198, v205
	s_waitcnt lgkmcnt(4)
	v_mfma_f32_32x32x16_bf16 v[82:97], v[242:245], v[122:125], v[82:97]
	ds_read_b128 v[242:245], v210 offset:22080
	s_waitcnt lgkmcnt(4)
	v_mfma_f32_32x32x16_bf16 v[82:97], v[246:249], v[126:129], v[82:97]
	ds_read_b128 v[246:249], v210 offset:22112
	s_waitcnt lgkmcnt(2)
	v_max3_f32 v211, v204, v205, v206
	v_sub_f32_e32 v206, v204, v211
	v_cmp_gt_f32_e32 vcc, 0xc1000000, v206
	s_cbranch_vccz .Llazy0_1
	v_exp_f32_e32 v206, v206
	s_nop 0
	s_and_saveexec_b64 s[2:3], s[6:7]
	ds_write_b32 v197, v206
	s_or_b64 exec, exec, s[2:3]
	s_waitcnt lgkmcnt(0)
	v_add_u32_e32 v204, s27, v80
	ds_read_b128 v[212:215], v204 offset:96
	ds_read_b128 v[234:237], v204 offset:64
	ds_read_b128 v[226:229], v204 offset:32
	ds_read_b128 v[230:233], v204
	s_waitcnt lgkmcnt(3)
	v_pk_mul_f32 v[12:13], v[12:13], v[212:213]
	s_waitcnt lgkmcnt(2)
	v_pk_mul_f32 v[8:9], v[8:9], v[234:235]
	s_waitcnt lgkmcnt(1)
	v_pk_mul_f32 v[4:5], v[4:5], v[226:227]
	v_pk_mul_f32 v[14:15], v[14:15], v[214:215]
	v_pk_mul_f32 v[10:11], v[10:11], v[236:237]
	v_pk_mul_f32 v[6:7], v[6:7], v[228:229]
	s_waitcnt lgkmcnt(0)
	v_pk_mul_f32 v[2:3], v[2:3], v[232:233]
	v_pk_mul_f32 v[0:1], v[0:1], v[230:231]
	v_pk_mul_f32 v[28:29], v[28:29], v[212:213]
	v_pk_mul_f32 v[24:25], v[24:25], v[234:235]
	v_pk_mul_f32 v[20:21], v[20:21], v[226:227]
	v_pk_mul_f32 v[30:31], v[30:31], v[214:215]
	v_pk_mul_f32 v[26:27], v[26:27], v[236:237]
	v_pk_mul_f32 v[22:23], v[22:23], v[228:229]
	v_pk_mul_f32 v[18:19], v[18:19], v[232:233]
	v_pk_mul_f32 v[16:17], v[16:17], v[230:231]
	v_pk_mul_f32 v[44:45], v[44:45], v[212:213]
	v_pk_mul_f32 v[40:41], v[40:41], v[234:235]
	v_pk_mul_f32 v[36:37], v[36:37], v[226:227]
	v_pk_mul_f32 v[46:47], v[46:47], v[214:215]
	v_pk_mul_f32 v[42:43], v[42:43], v[236:237]
	v_pk_mul_f32 v[38:39], v[38:39], v[228:229]
	v_pk_mul_f32 v[34:35], v[34:35], v[232:233]
	v_pk_mul_f32 v[32:33], v[32:33], v[230:231]
	v_pk_mul_f32 v[60:61], v[60:61], v[212:213]
	v_pk_mul_f32 v[56:57], v[56:57], v[234:235]
	v_pk_mul_f32 v[52:53], v[52:53], v[226:227]
	v_pk_mul_f32 v[62:63], v[62:63], v[214:215]
	v_pk_mul_f32 v[58:59], v[58:59], v[236:237]
	v_pk_mul_f32 v[54:55], v[54:55], v[228:229]
	v_pk_mul_f32 v[50:51], v[50:51], v[232:233]
	v_pk_mul_f32 v[48:49], v[48:49], v[230:231]

; DI float shx(float v, int o, int lane) { return __int_as_float(__builtin_amdgcn_ds_bpermute((lane ^ o) << 2, __float_as_int(v))); }
; DI int crow(int i, int hh) { return (i & 3) + 8 * (i >> 2) + 4 * hh; }
; #define MFMA32(a, b, c) __builtin_amdgcn_mfma_f32_32x32x16_bf16((a), (b), (c), 0, 0, 0)
; DI void attn_item(CArgs& a, LAS unsigned char* lds, int l, int b, int h, int qb, int tid_, int wave, int lane_) {
;     ...
;             for (int ks = 0; ks < 8; ++ks) p = MFMA32(lds_b128(Ks + (32 * kt + r) * 136 + 16 * ks + 8 * hh), qf[ks], p);
; #pragma unroll
;             for (int ks = 0; ks < 4; ++ks) p = MFMA32(lds_b128(Rs + (32 * kt + r) * 72 + 16 * ks + 8 * hh), qf[8 + ks], p);
;             if (j >= 4 * qb) {
; #pragma unroll
;                 for (int i = 0; i < 16; ++i) { const int key = 64 * j + 32 * kt + crow(i, hh); if (key > qloc) p[i] = -INFINITY; } }
;             float tmax = p[0];
; #pragma unroll
;             for (int i = 1; i < 16; ++i) tmax = fmaxf(tmax, p[i]);
;             tmax = fmaxf(tmax, shx(tmax, 32, lane));
;             const float m_new = fmaxf(m_run, tmax), alpha = __builtin_amdgcn_exp2f(m_run - m_new); m_run = m_new;
;             float rsum = 0.f;
; #pragma unroll
;             for (int i = 0; i < 16; ++i) { const float e = __builtin_amdgcn_exp2f(p[i] - m_new); p[i] = e; rsum += e; }
;             l_run = l_run * alpha + rsum;
;             if (__any(alpha != 1.f)) {
;                 if (hh == 0) scr[r] = alpha;
;                 asm volatile("s_waitcnt lgkmcnt(0)" ::: "memory");
; #pragma unroll
;                 for (int i = 0; i < 16; ++i) { const float ai = scr[crow(i, hh)]; o[0][i] *= ai; o[1][i] *= ai; o[2][i] *= ai; o[3][i] *= ai; }
;             }
.LBB0_329:
	v_max_f32_e32 v204, v83, v83
	v_max_f32_e32 v208, v82, v82
	v_max_f32_e32 v204, v208, v204
	s_waitcnt lgkmcnt(3)
	v_mfma_f32_32x32x16_bf16 v[0:15], v[72:75], v[68:71], v[0:15]
	v_max3_f32 v204, v204, v84, v85
	v_max3_f32 v204, v204, v86, v87
	v_max3_f32 v204, v204, v88, v89
	v_max3_f32 v204, v204, v90, v91
	s_waitcnt lgkmcnt(2)
	v_mfma_f32_32x32x16_bf16 v[16:31], v[72:75], v[76:79], v[16:31]
	v_max3_f32 v204, v204, v92, v93
	v_max3_f32 v204, v204, v94, v95
	v_max3_f32 v204, v204, v96, v97
	ds_bpermute_b32 v208, v198, v204
	s_waitcnt lgkmcnt(2)
	v_mfma_f32_32x32x16_bf16 v[32:47], v[72:75], v[216:219], v[32:47]
	s_waitcnt lgkmcnt(1)
	v_mfma_f32_32x32x16_bf16 v[48:63], v[72:75], v[238:241], v[48:63]
	s_waitcnt lgkmcnt(0)
	v_max3_f32 v204, v211, v204, v208
	v_sub_f32_e32 v208, v211, v204
	v_cmp_gt_f32_e32 vcc, 0xc1000000, v208
	s_cbranch_vccz .Llazy1_1
	v_exp_f32_e32 v208, v208
	s_nop 0
	s_and_saveexec_b64 s[0:1], s[6:7]
	ds_write_b32 v197, v208
	s_or_b64 exec, exec, s[0:1]
	s_waitcnt lgkmcnt(0)
	v_add_u32_e32 v209, s27, v80
	ds_read_b128 v[216:219], v209 offset:96
	ds_read_b128 v[238:241], v209 offset:64
	ds_read_b128 v[242:245], v209 offset:32
	ds_read_b128 v[246:249], v209
	s_waitcnt lgkmcnt(3)
	v_pk_mul_f32 v[12:13], v[12:13], v[216:217]
	s_waitcnt lgkmcnt(2)
	v_pk_mul_f32 v[8:9], v[8:9], v[238:239]
	s_waitcnt lgkmcnt(1)
	v_pk_mul_f32 v[4:5], v[4:5], v[242:243]
	v_pk_mul_f32 v[14:15], v[14:15], v[218:219]
	v_pk_mul_f32 v[10:11], v[10:11], v[240:241]
	v_pk_mul_f32 v[6:7], v[6:7], v[244:245]
	s_waitcnt lgkmcnt(0)
	v_pk_mul_f32 v[2:3], v[2:3], v[248:249]
	v_pk_mul_f32 v[0:1], v[0:1], v[246:247]
	v_pk_mul_f32 v[28:29], v[28:29], v[216:217]
	v_pk_mul_f32 v[24:25], v[24:25], v[238:239]
	v_pk_mul_f32 v[20:21], v[20:21], v[242:243]
	v_pk_mul_f32 v[30:31], v[30:31], v[218:219]
	v_pk_mul_f32 v[26:27], v[26:27], v[240:241]
	v_pk_mul_f32 v[22:23], v[22:23], v[244:245]
	v_pk_mul_f32 v[18:19], v[18:19], v[248:249]
	v_pk_mul_f32 v[16:17], v[16:17], v[246:247]
	v_pk_mul_f32 v[44:45], v[44:45], v[216:217]
	v_pk_mul_f32 v[40:41], v[40:41], v[238:239]
	v_pk_mul_f32 v[36:37], v[36:37], v[242:243]
	v_pk_mul_f32 v[46:47], v[46:47], v[218:219]
	v_pk_mul_f32 v[42:43], v[42:43], v[240:241]
	v_pk_mul_f32 v[38:39], v[38:39], v[244:245]
	v_pk_mul_f32 v[34:35], v[34:35], v[248:249]
	v_pk_mul_f32 v[32:33], v[32:33], v[246:247]
	v_pk_mul_f32 v[60:61], v[60:61], v[216:217]
	v_pk_mul_f32 v[56:57], v[56:57], v[238:239]
	v_pk_mul_f32 v[52:53], v[52:53], v[242:243]
	v_pk_mul_f32 v[62:63], v[62:63], v[218:219]
	v_pk_mul_f32 v[58:59], v[58:59], v[240:241]
	v_pk_mul_f32 v[54:55], v[54:55], v[244:245]
	v_pk_mul_f32 v[50:51], v[50:51], v[248:249]
	v_pk_mul_f32 v[48:49], v[48:49], v[246:247]
